# combo6: combo1 plus the per-XCD generation atomic removed from the barrier leader path (followers poll the top generation word)
# speedup vs baseline: 1.0165x; 1.0165x over previous
; __device__ __forceinline__ unsigned xb_ld(unsigned* p)              { return __hip_atomic_load(p, __ATOMIC_RELAXED, __HIP_MEMORY_SCOPE_AGENT); }
; __device__ __forceinline__ unsigned xb_add(unsigned* p, unsigned v) { return __hip_atomic_fetch_add(p, v, __ATOMIC_RELAXED, __HIP_MEMORY_SCOPE_AGENT); }
; #define XB_SPIN(cond, bar) do { unsigned _sp = 0; while (cond) { __builtin_amdgcn_s_sleep(1); \
;     if ((++_sp & 255u) == 0u) { if (xb_ld(&(bar)[XB_TMO])) break; if (_sp > XB_SPIN_CAP) { atomicAdd(&(bar)[XB_TMO], 1u); break; } } } } while (0)
; __device__ __forceinline__ void xcd_barrier(const XcdBarrier& b) {
;     ...
;             __builtin_amdgcn_fence(__ATOMIC_RELEASE, "agent");
;             asm volatile("s_waitcnt vmcnt(0)" ::: "memory");
;             const unsigned og = xb_add(&bar[XB_TOP], 1u);
;             const unsigned tg = og / nx;
;             if (og + 1u == (tg + 1u) * nx) xb_add(&bar[XB_TOPGEN], 1u);
;             else XB_SPIN(xb_ld(&bar[XB_TOPGEN]) == tg, bar);
;             __builtin_amdgcn_fence(__ATOMIC_ACQUIRE, "agent");
;             xb_add(&bar[XB_XGEN(b.x)], 1u);
;             asm volatile("s_waitcnt vmcnt(0)" ::: "memory");
.LBB0_123:
	s_or_b64 exec, exec, s[4:5]
	s_mov_b64 s[4:5], exec
	v_mbcnt_lo_u32_b32 v0, s4, 0
	v_mbcnt_hi_u32_b32 v0, s5, v0
	v_cmp_eq_u32_e32 vcc, 0, v0
	s_waitcnt vmcnt(0)
	buffer_inv sc1
	s_and_saveexec_b64 s[6:7], vcc
	s_cbranch_execz .LBB0_125
	s_bcnt1_i32_b64 s4, s[4:5]
	v_mov_b32_e32 v0, 0x2000
	v_mov_b32_e32 v1, s4
.LBB0_125:
	s_or_b64 exec, exec, s[6:7]
	s_waitcnt vmcnt(0)

; __device__ __forceinline__ unsigned xb_ld(unsigned* p)              { return __hip_atomic_load(p, __ATOMIC_RELAXED, __HIP_MEMORY_SCOPE_AGENT); }
; __device__ __forceinline__ unsigned xb_add(unsigned* p, unsigned v) { return __hip_atomic_fetch_add(p, v, __ATOMIC_RELAXED, __HIP_MEMORY_SCOPE_AGENT); }
; #define XB_SPIN(cond, bar) do { unsigned _sp = 0; while (cond) { __builtin_amdgcn_s_sleep(1); \
;     if ((++_sp & 255u) == 0u) { if (xb_ld(&(bar)[XB_TMO])) break; if (_sp > XB_SPIN_CAP) { atomicAdd(&(bar)[XB_TMO], 1u); break; } } } } while (0)
; __device__ __forceinline__ void xcd_barrier(const XcdBarrier& b) {
;     ...
;             __builtin_amdgcn_fence(__ATOMIC_RELEASE, "agent");
;             asm volatile("s_waitcnt vmcnt(0)" ::: "memory");
;             const unsigned og = xb_add(&bar[XB_TOP], 1u);
;             const unsigned tg = og / nx;
;             if (og + 1u == (tg + 1u) * nx) xb_add(&bar[XB_TOPGEN], 1u);
;             else XB_SPIN(xb_ld(&bar[XB_TOPGEN]) == tg, bar);
;             __builtin_amdgcn_fence(__ATOMIC_ACQUIRE, "agent");
;             xb_add(&bar[XB_XGEN(b.x)], 1u);
;             asm volatile("s_waitcnt vmcnt(0)" ::: "memory");
.LBB0_807:
	s_or_b64 exec, exec, s[4:5]
	s_mov_b64 s[4:5], exec
	v_mbcnt_lo_u32_b32 v0, s4, 0
	v_mbcnt_hi_u32_b32 v0, s5, v0
	v_cmp_eq_u32_e32 vcc, 0, v0
	s_waitcnt vmcnt(0)
	buffer_inv sc1
	s_and_saveexec_b64 s[6:7], vcc
	s_cbranch_execz .LBB0_809
	s_bcnt1_i32_b64 s4, s[4:5]
	v_mov_b32_e32 v0, 0x2000
	v_mov_b32_e32 v1, s4
.LBB0_809:
	s_or_b64 exec, exec, s[6:7]
	s_waitcnt vmcnt(0)

; __device__ __forceinline__ unsigned xb_ld(unsigned* p)              { return __hip_atomic_load(p, __ATOMIC_RELAXED, __HIP_MEMORY_SCOPE_AGENT); }
; __device__ __forceinline__ unsigned xb_add(unsigned* p, unsigned v) { return __hip_atomic_fetch_add(p, v, __ATOMIC_RELAXED, __HIP_MEMORY_SCOPE_AGENT); }
; #define XB_SPIN(cond, bar) do { unsigned _sp = 0; while (cond) { __builtin_amdgcn_s_sleep(1); \
;     if ((++_sp & 255u) == 0u) { if (xb_ld(&(bar)[XB_TMO])) break; if (_sp > XB_SPIN_CAP) { atomicAdd(&(bar)[XB_TMO], 1u); break; } } } } while (0)
; __device__ __forceinline__ void xcd_barrier(const XcdBarrier& b) {
;     ...
;             __builtin_amdgcn_fence(__ATOMIC_RELEASE, "agent");
;             asm volatile("s_waitcnt vmcnt(0)" ::: "memory");
;             const unsigned og = xb_add(&bar[XB_TOP], 1u);
;             const unsigned tg = og / nx;
;             if (og + 1u == (tg + 1u) * nx) xb_add(&bar[XB_TOPGEN], 1u);
;             else XB_SPIN(xb_ld(&bar[XB_TOPGEN]) == tg, bar);
;             __builtin_amdgcn_fence(__ATOMIC_ACQUIRE, "agent");
;             xb_add(&bar[XB_XGEN(b.x)], 1u);
;             asm volatile("s_waitcnt vmcnt(0)" ::: "memory");
.LBB0_924:
	s_or_b64 exec, exec, s[4:5]
	s_mov_b64 s[4:5], exec
	v_mbcnt_lo_u32_b32 v0, s4, 0
	v_mbcnt_hi_u32_b32 v0, s5, v0
	v_cmp_eq_u32_e32 vcc, 0, v0
	s_waitcnt vmcnt(0)
	buffer_inv sc1
	s_and_saveexec_b64 s[6:7], vcc
	s_cbranch_execz .LBB0_926
	s_bcnt1_i32_b64 s4, s[4:5]
	v_mov_b32_e32 v0, 0x2000
	v_mov_b32_e32 v1, s4
.LBB0_926:
	s_or_b64 exec, exec, s[6:7]
	s_waitcnt vmcnt(0)

; __device__ __forceinline__ unsigned xb_ld(unsigned* p)              { return __hip_atomic_load(p, __ATOMIC_RELAXED, __HIP_MEMORY_SCOPE_AGENT); }
; __device__ __forceinline__ unsigned xb_add(unsigned* p, unsigned v) { return __hip_atomic_fetch_add(p, v, __ATOMIC_RELAXED, __HIP_MEMORY_SCOPE_AGENT); }
; #define XB_SPIN(cond, bar) do { unsigned _sp = 0; while (cond) { __builtin_amdgcn_s_sleep(1); \
;     if ((++_sp & 255u) == 0u) { if (xb_ld(&(bar)[XB_TMO])) break; if (_sp > XB_SPIN_CAP) { atomicAdd(&(bar)[XB_TMO], 1u); break; } } } } while (0)
; __device__ __forceinline__ void xcd_barrier(const XcdBarrier& b) {
;     ...
;             __builtin_amdgcn_fence(__ATOMIC_RELEASE, "agent");
;             asm volatile("s_waitcnt vmcnt(0)" ::: "memory");
;             const unsigned og = xb_add(&bar[XB_TOP], 1u);
;             const unsigned tg = og / nx;
;             if (og + 1u == (tg + 1u) * nx) xb_add(&bar[XB_TOPGEN], 1u);
;             else XB_SPIN(xb_ld(&bar[XB_TOPGEN]) == tg, bar);
;             __builtin_amdgcn_fence(__ATOMIC_ACQUIRE, "agent");
;             xb_add(&bar[XB_XGEN(b.x)], 1u);
;             asm volatile("s_waitcnt vmcnt(0)" ::: "memory");
.LBB0_1021:
	s_or_b64 exec, exec, s[4:5]
	s_mov_b64 s[4:5], exec
	v_mbcnt_lo_u32_b32 v0, s4, 0
	v_mbcnt_hi_u32_b32 v0, s5, v0
	v_cmp_eq_u32_e32 vcc, 0, v0
	s_waitcnt vmcnt(0)
	buffer_inv sc1
	s_and_saveexec_b64 s[6:7], vcc
	s_cbranch_execz .LBB0_1023
	s_bcnt1_i32_b64 s4, s[4:5]
	v_mov_b32_e32 v0, 0x2000
	v_mov_b32_e32 v1, s4
.LBB0_1023:
	s_or_b64 exec, exec, s[6:7]
	s_waitcnt vmcnt(0)
